# EpiUp rope epilogue: cos/sin rows of the next block loaded one block ahead into a spare buffer with counted vmcnt
# baseline (speedup 1.0000x reference)
;     __device__ __forceinline__ float ssq8(int row, int which) const { const f32x4 a = *(const f32x4*)(ssqp + row * 16 + which * 8), b = *(const f32x4*)(ssqp + row * 16 + which * 8 + 4); return ((a[0] + a[1]) + (a[2] + a[3])) + ((b[0] + b[1]) + (b[2] + b[3])); }
;     __device__ __forceinline__ void operator()(const AccT& acc, const pg8::Unit& u, int wr, int wc, int fr, int fq) const {
;     ...
;                     const float rs = rsqrtf(ssq8(row, 0) * (1.0f / 512) + EPSN) * QS_MLA;
; #pragma unroll
;                     for (int bj = 0; bj < 2; ++bj)
;                         *(u32x4*)(Qm + (size_t)row * 1536 + (2 * u.pn + bj) * 192 + wc * 32 + 8 * fq) = pack8s(acc[ai][bj][m][0], acc[ai][bj][m][1], rs);
;                 } else if (u.pn < 6) {
;                     const float rs = rsqrtf(ssq8(row, 0) * (1.0f / 512) + EPSN) * QS_MLA;
;                     const int head = 4 * (u.pn - 4) + wc;
;                     const f32x4 c0 = *(const f32x4*)(cosT + row * 32 + 8 * fq), c1 = *(const f32x4*)(cosT + row * 32 + 8 * fq + 4);
;                     const f32x4 s0 = *(const f32x4*)(sinT + row * 32 + 8 * fq), s1 = *(const f32x4*)(sinT + row * 32 + 8 * fq + 4);
;                     const f32x4 x1a = acc[ai][0][m][0] * rs, x1b = acc[ai][0][m][1] * rs, x2a = acc[ai][1][m][0] * rs, x2b = acc[ai][1][m][1] * rs;
;                     const f32x4 y1a = x1a * c0 - x2a * s0, y1b = x1b * c1 - x2b * s1, y2a = x2a * c0 + x1a * s0, y2b = x2b * c1 + x1b * s1;
;                     *(u32x4*)(Qm + (size_t)row * 1536 + head * 192 + 128 + 8 * fq) = pack8s(y1a, y1b, 1.0f);
;                     *(u32x4*)(Qm + (size_t)row * 1536 + head * 192 + 160 + 8 * fq) = pack8s(y2a, y2b, 1.0f);
.LBB0_1431:
	s_andn2_b64 vcc, exec, s[18:19]
	s_cbranch_vccnz .LBB0_1433
	s_mov_b32 s2, 0x800000
	s_nop 0
	s_nop 0
	v_mov_b32_e32 v0, v248
	v_fmamk_f32 v0, v0, 0x3b000000, v212
	v_cmp_gt_f32_e32 vcc, s2, v0
	v_mul_f32_e32 v130, 0x4b800000, v0
	s_movk_i32 s2, 0xc00
	v_cndmask_b32_e32 v0, v0, v130, vcc
	v_rsq_f32_e32 v0, v0
	s_nop 0
	v_mul_f32_e32 v130, 0x45800000, v0
	v_cndmask_b32_e32 v0, v0, v130, vcc
	v_lshlrev_b32_e32 v130, 5, v152
	v_ashrrev_i32_e32 v131, 31, v130
	v_lshlrev_b64 v[160:161], 2, v[130:131]
	v_lshl_add_u64 v[156:157], v[144:145], 0, v[160:161]
	v_lshl_add_u64 v[160:161], v[146:147], 0, v[160:161]
	v_mov_b64_e32 v[224:225], v[156:157]
	v_mov_b64_e32 v[226:227], v[160:161]
	global_load_dwordx4 v[130:133], v[156:157], off offset:16
	s_nop 0
	global_load_dwordx4 v[156:159], v[156:157], off
	s_nop 0
	global_load_dwordx4 v[166:169], v[160:161], off offset:16
	s_nop 0
	global_load_dwordx4 v[160:163], v[160:161], off
	v_mul_f32_e32 v0, 0x3dd53b94, v0
	v_pk_mul_f32 v[170:171], v[126:127], v[0:1] op_sel_hi:[1,0]
	v_pk_mul_f32 v[172:173], v[128:129], v[0:1] op_sel_hi:[1,0]
	v_pk_mul_f32 v[178:179], v[120:121], v[0:1] op_sel_hi:[1,0]
	v_pk_mul_f32 v[180:181], v[118:119], v[0:1] op_sel_hi:[1,0]
	v_pk_mul_f32 v[174:175], v[122:123], v[0:1] op_sel_hi:[1,0]
	v_pk_mul_f32 v[184:185], v[114:115], v[0:1] op_sel_hi:[1,0]
	v_pk_mul_f32 v[176:177], v[124:125], v[0:1] op_sel_hi:[1,0]
	v_pk_mul_f32 v[182:183], v[116:117], v[0:1] op_sel_hi:[1,0]
	v_lshlrev_b32_e32 v0, 1, v142
	s_waitcnt vmcnt(0)
	s_mov_b32 s100, 2048
	s_mov_b32 s101, 0
	v_lshl_add_u64 v[224:225], v[224:225], 0, s[100:101]
	v_lshl_add_u64 v[226:227], v[226:227], 0, s[100:101]
	global_load_dwordx4 v[194:197], v[224:225], off offset:16
	global_load_dwordx4 v[198:201], v[224:225], off
	global_load_dwordx4 v[202:205], v[226:227], off offset:16
	global_load_dwordx4 v[206:209], v[226:227], off
	v_pk_mul_f32 v[190:191], v[166:167], v[184:185]
	v_pk_mul_f32 v[186:187], v[160:161], v[180:181]
	v_pk_mul_f32 v[188:189], v[162:163], v[178:179]
	v_pk_mul_f32 v[160:161], v[160:161], v[170:171]
	v_pk_mul_f32 v[162:163], v[162:163], v[172:173]
	v_pk_fma_f32 v[188:189], v[158:159], v[172:173], v[188:189] neg_lo:[0,0,1] neg_hi:[0,0,1]
	v_pk_fma_f32 v[158:159], v[158:159], v[178:179], v[162:163]
	v_pk_fma_f32 v[162:163], v[156:157], v[180:181], v[160:161]
	v_pk_mul_f32 v[160:161], v[166:167], v[174:175]
	v_mov_b64_e32 v[166:167], s[44:45]
	v_mad_i64_i32 v[166:167], s[2:3], v152, s2, v[166:167]
	v_pk_fma_f32 v[186:187], v[156:157], v[170:171], v[186:187] neg_lo:[0,0,1] neg_hi:[0,0,1]
	v_pk_mul_f32 v[192:193], v[168:169], v[182:183]
	v_pk_mul_f32 v[156:157], v[168:169], v[176:177]
	v_lshl_add_u64 v[166:167], s[0:1], 1, v[166:167]
	v_pk_fma_f32 v[192:193], v[132:133], v[176:177], v[192:193] neg_lo:[0,0,1] neg_hi:[0,0,1]
	v_pk_fma_f32 v[190:191], v[130:131], v[174:175], v[190:191] neg_lo:[0,0,1] neg_hi:[0,0,1]
	v_pk_fma_f32 v[156:157], v[132:133], v[182:183], v[156:157]
	v_pk_fma_f32 v[160:161], v[130:131], v[184:185], v[160:161]
	v_cvt_pk_bf16_f32 v130, v186, v187
	v_cvt_pk_bf16_f32 v131, v188, v189
	v_cvt_pk_bf16_f32 v132, v190, v191
	v_cvt_pk_bf16_f32 v133, v192, v193
	v_lshl_add_u64 v[168:169], v[166:167], 0, v[0:1]
	s_mov_b64 s[2:3], 0x140
	global_store_dwordx4 v[168:169], v[130:133], off offset:256
	s_nop 1
	v_cvt_pk_bf16_f32 v130, v162, v163
	v_cvt_pk_bf16_f32 v131, v158, v159
	v_cvt_pk_bf16_f32 v132, v160, v161
	v_cvt_pk_bf16_f32 v133, v156, v157
	v_lshl_add_u64 v[156:157], v[166:167], 0, s[2:3]

;     __device__ __forceinline__ float ssq8(int row, int which) const { const f32x4 a = *(const f32x4*)(ssqp + row * 16 + which * 8), b = *(const f32x4*)(ssqp + row * 16 + which * 8 + 4); return ((a[0] + a[1]) + (a[2] + a[3])) + ((b[0] + b[1]) + (b[2] + b[3])); }
;     __device__ __forceinline__ void operator()(const AccT& acc, const pg8::Unit& u, int wr, int wc, int fr, int fq) const {
;     ...
;                 } else if (u.pn < 6) {
;                     const float rs = rsqrtf(ssq8(row, 0) * (1.0f / 512) + EPSN) * QS_MLA;
;                     const int head = 4 * (u.pn - 4) + wc;
;                     const f32x4 c0 = *(const f32x4*)(cosT + row * 32 + 8 * fq), c1 = *(const f32x4*)(cosT + row * 32 + 8 * fq + 4);
;                     const f32x4 s0 = *(const f32x4*)(sinT + row * 32 + 8 * fq), s1 = *(const f32x4*)(sinT + row * 32 + 8 * fq + 4);
;                     const f32x4 x1a = acc[ai][0][m][0] * rs, x1b = acc[ai][0][m][1] * rs, x2a = acc[ai][1][m][0] * rs, x2b = acc[ai][1][m][1] * rs;
;                     const f32x4 y1a = x1a * c0 - x2a * s0, y1b = x1b * c1 - x2b * s1, y2a = x2a * c0 + x1a * s0, y2b = x2b * c1 + x1b * s1;
;                     *(u32x4*)(Qm + (size_t)row * 1536 + head * 192 + 128 + 8 * fq) = pack8s(y1a, y1b, 1.0f);
;                     *(u32x4*)(Qm + (size_t)row * 1536 + head * 192 + 160 + 8 * fq) = pack8s(y2a, y2b, 1.0f);
.LBB0_1439:
	s_andn2_b64 vcc, exec, s[8:9]
	s_cbranch_vccnz .LBB0_1441
	s_mov_b32 s2, 0x800000
	s_nop 0
	s_nop 0
	v_mov_b32_e32 v114, v249
	v_fmamk_f32 v114, v114, 0x3b000000, v212
	v_cmp_gt_f32_e32 vcc, s2, v114
	v_mul_f32_e32 v115, 0x4b800000, v114
	s_movk_i32 s2, 0xc00
	v_cndmask_b32_e32 v114, v114, v115, vcc
	v_rsq_f32_e32 v114, v114
	s_nop 0
	v_mul_f32_e32 v115, 0x45800000, v114
	v_cndmask_b32_e32 v114, v114, v115, vcc
	v_mul_f32_e32 v154, 0x3dd53b94, v114
	v_lshlrev_b32_e32 v114, 5, v118
	v_ashrrev_i32_e32 v115, 31, v114
	v_lshlrev_b64 v[126:127], 2, v[114:115]
	v_lshl_add_u64 v[122:123], v[144:145], 0, v[126:127]
	v_lshl_add_u64 v[126:127], v[146:147], 0, v[126:127]
	v_pk_mul_f32 v[156:157], v[110:111], v[154:155] op_sel_hi:[1,0]
	v_pk_mul_f32 v[158:159], v[112:113], v[154:155] op_sel_hi:[1,0]
	v_pk_mul_f32 v[166:167], v[104:105], v[154:155] op_sel_hi:[1,0]
	v_pk_mul_f32 v[168:169], v[102:103], v[154:155] op_sel_hi:[1,0]
	v_pk_mul_f32 v[160:161], v[106:107], v[154:155] op_sel_hi:[1,0]
	v_pk_mul_f32 v[162:163], v[108:109], v[154:155] op_sel_hi:[1,0]
	v_pk_mul_f32 v[170:171], v[100:101], v[154:155] op_sel_hi:[1,0]
	v_pk_mul_f32 v[154:155], v[98:99], v[154:155] op_sel_hi:[1,0]
	s_waitcnt vmcnt(2)
	v_mov_b64_e32 v[114:115], v[194:195]
	v_mov_b64_e32 v[116:117], v[196:197]
	v_mov_b64_e32 v[122:123], v[198:199]
	v_mov_b64_e32 v[124:125], v[200:201]
	v_mov_b64_e32 v[130:131], v[202:203]
	v_mov_b64_e32 v[132:133], v[204:205]
	v_mov_b64_e32 v[126:127], v[206:207]
	v_mov_b64_e32 v[128:129], v[208:209]
	s_mov_b32 s100, 2048
	s_mov_b32 s101, 0
	v_lshl_add_u64 v[224:225], v[224:225], 0, s[100:101]
	v_lshl_add_u64 v[226:227], v[226:227], 0, s[100:101]
	global_load_dwordx4 v[194:197], v[224:225], off offset:16
	global_load_dwordx4 v[198:201], v[224:225], off
	global_load_dwordx4 v[202:205], v[226:227], off offset:16
	global_load_dwordx4 v[206:209], v[226:227], off
	v_pk_mul_f32 v[178:179], v[132:133], v[170:171]
	v_pk_mul_f32 v[172:173], v[126:127], v[168:169]
	v_pk_mul_f32 v[174:175], v[128:129], v[166:167]
	v_pk_mul_f32 v[126:127], v[126:127], v[156:157]
	v_pk_mul_f32 v[128:129], v[128:129], v[158:159]
	v_pk_fma_f32 v[174:175], v[124:125], v[158:159], v[174:175] neg_lo:[0,0,1] neg_hi:[0,0,1]
	v_pk_mul_f32 v[176:177], v[130:131], v[154:155]
	v_pk_fma_f32 v[124:125], v[124:125], v[166:167], v[128:129]
	v_pk_fma_f32 v[128:129], v[122:123], v[168:169], v[126:127]
	v_pk_mul_f32 v[126:127], v[130:131], v[160:161]
	v_mov_b64_e32 v[130:131], s[44:45]
	v_mad_i64_i32 v[130:131], s[2:3], v118, s2, v[130:131]
	v_pk_fma_f32 v[172:173], v[122:123], v[156:157], v[172:173] neg_lo:[0,0,1] neg_hi:[0,0,1]
	v_pk_mul_f32 v[122:123], v[132:133], v[162:163]
	v_lshl_add_u64 v[130:131], s[0:1], 1, v[130:131]
	v_pk_fma_f32 v[178:179], v[116:117], v[162:163], v[178:179] neg_lo:[0,0,1] neg_hi:[0,0,1]
	v_pk_fma_f32 v[176:177], v[114:115], v[160:161], v[176:177] neg_lo:[0,0,1] neg_hi:[0,0,1]
	v_pk_fma_f32 v[122:123], v[116:117], v[170:171], v[122:123]
	v_pk_fma_f32 v[126:127], v[114:115], v[154:155], v[126:127]
	v_cvt_pk_bf16_f32 v114, v172, v173
	v_cvt_pk_bf16_f32 v115, v174, v175
	v_cvt_pk_bf16_f32 v116, v176, v177
	v_cvt_pk_bf16_f32 v117, v178, v179
	v_lshl_add_u64 v[132:133], v[130:131], 0, v[0:1]
	s_mov_b64 s[2:3], 0x140
	global_store_dwordx4 v[132:133], v[114:117], off offset:256
	s_nop 1
	v_cvt_pk_bf16_f32 v114, v128, v129
	v_cvt_pk_bf16_f32 v115, v124, v125
	v_cvt_pk_bf16_f32 v116, v126, v127
	v_cvt_pk_bf16_f32 v117, v122, v123
	v_lshl_add_u64 v[122:123], v[130:131], 0, s[2:3]

;     __device__ __forceinline__ float ssq8(int row, int which) const { const f32x4 a = *(const f32x4*)(ssqp + row * 16 + which * 8), b = *(const f32x4*)(ssqp + row * 16 + which * 8 + 4); return ((a[0] + a[1]) + (a[2] + a[3])) + ((b[0] + b[1]) + (b[2] + b[3])); }
;     __device__ __forceinline__ void operator()(const AccT& acc, const pg8::Unit& u, int wr, int wc, int fr, int fq) const {
;     ...
;                 } else if (u.pn < 6) {
;                     const float rs = rsqrtf(ssq8(row, 0) * (1.0f / 512) + EPSN) * QS_MLA;
;                     const int head = 4 * (u.pn - 4) + wc;
;                     const f32x4 c0 = *(const f32x4*)(cosT + row * 32 + 8 * fq), c1 = *(const f32x4*)(cosT + row * 32 + 8 * fq + 4);
;                     const f32x4 s0 = *(const f32x4*)(sinT + row * 32 + 8 * fq), s1 = *(const f32x4*)(sinT + row * 32 + 8 * fq + 4);
;                     const f32x4 x1a = acc[ai][0][m][0] * rs, x1b = acc[ai][0][m][1] * rs, x2a = acc[ai][1][m][0] * rs, x2b = acc[ai][1][m][1] * rs;
;                     const f32x4 y1a = x1a * c0 - x2a * s0, y1b = x1b * c1 - x2b * s1, y2a = x2a * c0 + x1a * s0, y2b = x2b * c1 + x1b * s1;
;                     *(u32x4*)(Qm + (size_t)row * 1536 + head * 192 + 128 + 8 * fq) = pack8s(y1a, y1b, 1.0f);
;                     *(u32x4*)(Qm + (size_t)row * 1536 + head * 192 + 160 + 8 * fq) = pack8s(y2a, y2b, 1.0f);
.LBB0_1447:
	s_andn2_b64 vcc, exec, s[8:9]
	s_cbranch_vccnz .LBB0_1449
	s_mov_b32 s2, 0x800000
	s_nop 0
	s_nop 0
	v_mov_b32_e32 v98, v250
	v_fmamk_f32 v98, v98, 0x3b000000, v212
	v_cmp_gt_f32_e32 vcc, s2, v98
	v_mul_f32_e32 v99, 0x4b800000, v98
	s_movk_i32 s2, 0xc00
	v_cndmask_b32_e32 v98, v98, v99, vcc
	v_rsq_f32_e32 v98, v98
	s_nop 0
	v_mul_f32_e32 v99, 0x45800000, v98
	v_cndmask_b32_e32 v98, v98, v99, vcc
	v_mul_f32_e32 v118, 0x3dd53b94, v98
	v_lshlrev_b32_e32 v98, 5, v102
	v_ashrrev_i32_e32 v99, 31, v98
	v_lshlrev_b64 v[110:111], 2, v[98:99]
	v_lshl_add_u64 v[106:107], v[144:145], 0, v[110:111]
	v_lshl_add_u64 v[110:111], v[146:147], 0, v[110:111]
	v_pk_mul_f32 v[120:121], v[94:95], v[118:119] op_sel_hi:[1,0]
	v_pk_mul_f32 v[122:123], v[96:97], v[118:119] op_sel_hi:[1,0]
	v_pk_mul_f32 v[128:129], v[88:89], v[118:119] op_sel_hi:[1,0]
	v_pk_mul_f32 v[130:131], v[86:87], v[118:119] op_sel_hi:[1,0]
	v_pk_mul_f32 v[124:125], v[90:91], v[118:119] op_sel_hi:[1,0]
	v_pk_mul_f32 v[126:127], v[92:93], v[118:119] op_sel_hi:[1,0]
	v_pk_mul_f32 v[132:133], v[84:85], v[118:119] op_sel_hi:[1,0]
	v_pk_mul_f32 v[118:119], v[82:83], v[118:119] op_sel_hi:[1,0]
	s_waitcnt vmcnt(2)
	v_mov_b64_e32 v[98:99], v[194:195]
	v_mov_b64_e32 v[100:101], v[196:197]
	v_mov_b64_e32 v[106:107], v[198:199]
	v_mov_b64_e32 v[108:109], v[200:201]
	v_mov_b64_e32 v[114:115], v[202:203]
	v_mov_b64_e32 v[116:117], v[204:205]
	v_mov_b64_e32 v[110:111], v[206:207]
	v_mov_b64_e32 v[112:113], v[208:209]
	s_mov_b32 s100, 2048
	s_mov_b32 s101, 0
	v_lshl_add_u64 v[224:225], v[224:225], 0, s[100:101]
	v_lshl_add_u64 v[226:227], v[226:227], 0, s[100:101]
	global_load_dwordx4 v[194:197], v[224:225], off offset:16
	global_load_dwordx4 v[198:201], v[224:225], off
	global_load_dwordx4 v[202:205], v[226:227], off offset:16
	global_load_dwordx4 v[206:209], v[226:227], off
	v_pk_mul_f32 v[160:161], v[116:117], v[132:133]
	v_pk_mul_f32 v[154:155], v[110:111], v[130:131]
	v_pk_mul_f32 v[156:157], v[112:113], v[128:129]
	v_pk_mul_f32 v[110:111], v[110:111], v[120:121]
	v_pk_mul_f32 v[112:113], v[112:113], v[122:123]
	v_pk_fma_f32 v[156:157], v[108:109], v[122:123], v[156:157] neg_lo:[0,0,1] neg_hi:[0,0,1]
	v_pk_mul_f32 v[158:159], v[114:115], v[118:119]
	v_pk_fma_f32 v[108:109], v[108:109], v[128:129], v[112:113]
	v_pk_fma_f32 v[112:113], v[106:107], v[130:131], v[110:111]
	v_pk_mul_f32 v[110:111], v[114:115], v[124:125]
	v_mov_b64_e32 v[114:115], s[44:45]
	v_mad_i64_i32 v[114:115], s[2:3], v102, s2, v[114:115]
	v_pk_fma_f32 v[154:155], v[106:107], v[120:121], v[154:155] neg_lo:[0,0,1] neg_hi:[0,0,1]
	v_pk_mul_f32 v[106:107], v[116:117], v[126:127]
	v_lshl_add_u64 v[114:115], s[0:1], 1, v[114:115]
	v_pk_fma_f32 v[160:161], v[100:101], v[126:127], v[160:161] neg_lo:[0,0,1] neg_hi:[0,0,1]
	v_pk_fma_f32 v[158:159], v[98:99], v[124:125], v[158:159] neg_lo:[0,0,1] neg_hi:[0,0,1]
	v_pk_fma_f32 v[106:107], v[100:101], v[132:133], v[106:107]
	v_pk_fma_f32 v[110:111], v[98:99], v[118:119], v[110:111]
	v_cvt_pk_bf16_f32 v98, v154, v155
	v_cvt_pk_bf16_f32 v99, v156, v157
	v_cvt_pk_bf16_f32 v100, v158, v159
	v_cvt_pk_bf16_f32 v101, v160, v161
	v_lshl_add_u64 v[116:117], v[114:115], 0, v[0:1]
	s_mov_b64 s[2:3], 0x140
	global_store_dwordx4 v[116:117], v[98:101], off offset:256
	s_nop 1
	v_cvt_pk_bf16_f32 v98, v112, v113
	v_cvt_pk_bf16_f32 v99, v108, v109
	v_cvt_pk_bf16_f32 v100, v110, v111
	v_cvt_pk_bf16_f32 v101, v106, v107
	v_lshl_add_u64 v[106:107], v[114:115], 0, s[2:3]

;     __device__ __forceinline__ float ssq8(int row, int which) const { const f32x4 a = *(const f32x4*)(ssqp + row * 16 + which * 8), b = *(const f32x4*)(ssqp + row * 16 + which * 8 + 4); return ((a[0] + a[1]) + (a[2] + a[3])) + ((b[0] + b[1]) + (b[2] + b[3])); }
;     __device__ __forceinline__ void operator()(const AccT& acc, const pg8::Unit& u, int wr, int wc, int fr, int fq) const {
;     ...
;                 } else if (u.pn < 6) {
;                     const float rs = rsqrtf(ssq8(row, 0) * (1.0f / 512) + EPSN) * QS_MLA;
;                     const int head = 4 * (u.pn - 4) + wc;
;                     const f32x4 c0 = *(const f32x4*)(cosT + row * 32 + 8 * fq), c1 = *(const f32x4*)(cosT + row * 32 + 8 * fq + 4);
;                     const f32x4 s0 = *(const f32x4*)(sinT + row * 32 + 8 * fq), s1 = *(const f32x4*)(sinT + row * 32 + 8 * fq + 4);
;                     const f32x4 x1a = acc[ai][0][m][0] * rs, x1b = acc[ai][0][m][1] * rs, x2a = acc[ai][1][m][0] * rs, x2b = acc[ai][1][m][1] * rs;
;                     const f32x4 y1a = x1a * c0 - x2a * s0, y1b = x1b * c1 - x2b * s1, y2a = x2a * c0 + x1a * s0, y2b = x2b * c1 + x1b * s1;
;                     *(u32x4*)(Qm + (size_t)row * 1536 + head * 192 + 128 + 8 * fq) = pack8s(y1a, y1b, 1.0f);
;                     *(u32x4*)(Qm + (size_t)row * 1536 + head * 192 + 160 + 8 * fq) = pack8s(y2a, y2b, 1.0f);
.LBB0_1455:
	s_andn2_b64 vcc, exec, s[8:9]
	s_cbranch_vccnz .LBB0_1457
	s_mov_b32 s2, 0x800000
	s_nop 0
	s_nop 0
	v_mov_b32_e32 v82, v251
	v_fmamk_f32 v82, v82, 0x3b000000, v212
	v_cmp_gt_f32_e32 vcc, s2, v82
	v_mul_f32_e32 v83, 0x4b800000, v82
	s_movk_i32 s2, 0xc00
	v_cndmask_b32_e32 v82, v82, v83, vcc
	v_rsq_f32_e32 v82, v82
	s_nop 0
	v_mul_f32_e32 v83, 0x45800000, v82
	v_cndmask_b32_e32 v82, v82, v83, vcc
	v_mul_f32_e32 v102, 0x3dd53b94, v82
	v_lshlrev_b32_e32 v82, 5, v86
	v_ashrrev_i32_e32 v83, 31, v82
	v_lshlrev_b64 v[94:95], 2, v[82:83]
	v_lshl_add_u64 v[90:91], v[144:145], 0, v[94:95]
	v_lshl_add_u64 v[94:95], v[146:147], 0, v[94:95]
	v_pk_mul_f32 v[104:105], v[78:79], v[102:103] op_sel_hi:[1,0]
	v_pk_mul_f32 v[106:107], v[80:81], v[102:103] op_sel_hi:[1,0]
	v_pk_mul_f32 v[112:113], v[72:73], v[102:103] op_sel_hi:[1,0]
	v_pk_mul_f32 v[114:115], v[70:71], v[102:103] op_sel_hi:[1,0]
	v_pk_mul_f32 v[108:109], v[74:75], v[102:103] op_sel_hi:[1,0]
	v_pk_mul_f32 v[110:111], v[76:77], v[102:103] op_sel_hi:[1,0]
	v_pk_mul_f32 v[116:117], v[68:69], v[102:103] op_sel_hi:[1,0]
	v_pk_mul_f32 v[102:103], v[66:67], v[102:103] op_sel_hi:[1,0]
	s_waitcnt vmcnt(2)
	v_mov_b64_e32 v[82:83], v[194:195]
	v_mov_b64_e32 v[84:85], v[196:197]
	v_mov_b64_e32 v[90:91], v[198:199]
	v_mov_b64_e32 v[92:93], v[200:201]
	v_mov_b64_e32 v[98:99], v[202:203]
	v_mov_b64_e32 v[100:101], v[204:205]
	v_mov_b64_e32 v[94:95], v[206:207]
	v_mov_b64_e32 v[96:97], v[208:209]
	s_mov_b32 s100, 10240
	s_mov_b32 s101, 0
	v_lshl_add_u64 v[224:225], v[224:225], 0, s[100:101]
	v_lshl_add_u64 v[226:227], v[226:227], 0, s[100:101]
	global_load_dwordx4 v[194:197], v[224:225], off offset:16
	global_load_dwordx4 v[198:201], v[224:225], off
	global_load_dwordx4 v[202:205], v[226:227], off offset:16
	global_load_dwordx4 v[206:209], v[226:227], off
	v_pk_mul_f32 v[124:125], v[100:101], v[116:117]
	v_pk_mul_f32 v[118:119], v[94:95], v[114:115]
	v_pk_mul_f32 v[120:121], v[96:97], v[112:113]
	v_pk_mul_f32 v[94:95], v[94:95], v[104:105]
	v_pk_mul_f32 v[96:97], v[96:97], v[106:107]
	v_pk_fma_f32 v[120:121], v[92:93], v[106:107], v[120:121] neg_lo:[0,0,1] neg_hi:[0,0,1]
	v_pk_mul_f32 v[122:123], v[98:99], v[102:103]
	v_pk_fma_f32 v[92:93], v[92:93], v[112:113], v[96:97]
	v_pk_fma_f32 v[96:97], v[90:91], v[114:115], v[94:95]
	v_pk_mul_f32 v[94:95], v[98:99], v[108:109]
	v_mov_b64_e32 v[98:99], s[44:45]
	v_mad_i64_i32 v[98:99], s[2:3], v86, s2, v[98:99]
	v_pk_fma_f32 v[118:119], v[90:91], v[104:105], v[118:119] neg_lo:[0,0,1] neg_hi:[0,0,1]
	v_pk_mul_f32 v[90:91], v[100:101], v[110:111]
	v_lshl_add_u64 v[98:99], s[0:1], 1, v[98:99]
	v_pk_fma_f32 v[124:125], v[84:85], v[110:111], v[124:125] neg_lo:[0,0,1] neg_hi:[0,0,1]
	v_pk_fma_f32 v[122:123], v[82:83], v[108:109], v[122:123] neg_lo:[0,0,1] neg_hi:[0,0,1]
	v_pk_fma_f32 v[90:91], v[84:85], v[116:117], v[90:91]
	v_pk_fma_f32 v[94:95], v[82:83], v[102:103], v[94:95]
	v_cvt_pk_bf16_f32 v82, v118, v119
	v_cvt_pk_bf16_f32 v83, v120, v121
	v_cvt_pk_bf16_f32 v84, v122, v123
	v_cvt_pk_bf16_f32 v85, v124, v125
	v_lshl_add_u64 v[100:101], v[98:99], 0, v[0:1]
	s_mov_b64 s[2:3], 0x140
	global_store_dwordx4 v[100:101], v[82:85], off offset:256
	s_nop 1
	v_cvt_pk_bf16_f32 v82, v96, v97
	v_cvt_pk_bf16_f32 v83, v92, v93
	v_cvt_pk_bf16_f32 v84, v94, v95
	v_cvt_pk_bf16_f32 v85, v90, v91
	v_lshl_add_u64 v[90:91], v[98:99], 0, s[2:3]

;     __device__ __forceinline__ float ssq8(int row, int which) const { const f32x4 a = *(const f32x4*)(ssqp + row * 16 + which * 8), b = *(const f32x4*)(ssqp + row * 16 + which * 8 + 4); return ((a[0] + a[1]) + (a[2] + a[3])) + ((b[0] + b[1]) + (b[2] + b[3])); }
;     __device__ __forceinline__ void operator()(const AccT& acc, const pg8::Unit& u, int wr, int wc, int fr, int fq) const {
;     ...
;                 } else if (u.pn < 6) {
;                     const float rs = rsqrtf(ssq8(row, 0) * (1.0f / 512) + EPSN) * QS_MLA;
;                     const int head = 4 * (u.pn - 4) + wc;
;                     const f32x4 c0 = *(const f32x4*)(cosT + row * 32 + 8 * fq), c1 = *(const f32x4*)(cosT + row * 32 + 8 * fq + 4);
;                     const f32x4 s0 = *(const f32x4*)(sinT + row * 32 + 8 * fq), s1 = *(const f32x4*)(sinT + row * 32 + 8 * fq + 4);
;                     const f32x4 x1a = acc[ai][0][m][0] * rs, x1b = acc[ai][0][m][1] * rs, x2a = acc[ai][1][m][0] * rs, x2b = acc[ai][1][m][1] * rs;
;                     const f32x4 y1a = x1a * c0 - x2a * s0, y1b = x1b * c1 - x2b * s1, y2a = x2a * c0 + x1a * s0, y2b = x2b * c1 + x1b * s1;
;                     *(u32x4*)(Qm + (size_t)row * 1536 + head * 192 + 128 + 8 * fq) = pack8s(y1a, y1b, 1.0f);
;                     *(u32x4*)(Qm + (size_t)row * 1536 + head * 192 + 160 + 8 * fq) = pack8s(y2a, y2b, 1.0f);
.LBB0_1463:
	s_andn2_b64 vcc, exec, s[8:9]
	s_cbranch_vccnz .LBB0_1465
	s_mov_b32 s2, 0x800000
	s_nop 0
	s_nop 0
	v_mov_b32_e32 v66, v236
	v_fmamk_f32 v66, v66, 0x3b000000, v212
	v_cmp_gt_f32_e32 vcc, s2, v66
	v_mul_f32_e32 v67, 0x4b800000, v66
	s_movk_i32 s2, 0xc00
	v_cndmask_b32_e32 v66, v66, v67, vcc
	v_rsq_f32_e32 v66, v66
	s_nop 0
	v_mul_f32_e32 v67, 0x45800000, v66
	v_cndmask_b32_e32 v66, v66, v67, vcc
	v_mul_f32_e32 v86, 0x3dd53b94, v66
	v_lshlrev_b32_e32 v66, 5, v70
	v_ashrrev_i32_e32 v67, 31, v66
	v_lshlrev_b64 v[78:79], 2, v[66:67]
	v_lshl_add_u64 v[74:75], v[144:145], 0, v[78:79]
	v_lshl_add_u64 v[78:79], v[146:147], 0, v[78:79]
	v_pk_mul_f32 v[88:89], v[62:63], v[86:87] op_sel_hi:[1,0]
	v_pk_mul_f32 v[90:91], v[64:65], v[86:87] op_sel_hi:[1,0]
	v_pk_mul_f32 v[96:97], v[56:57], v[86:87] op_sel_hi:[1,0]
	v_pk_mul_f32 v[98:99], v[54:55], v[86:87] op_sel_hi:[1,0]
	v_pk_mul_f32 v[92:93], v[58:59], v[86:87] op_sel_hi:[1,0]
	v_pk_mul_f32 v[94:95], v[60:61], v[86:87] op_sel_hi:[1,0]
	v_pk_mul_f32 v[100:101], v[52:53], v[86:87] op_sel_hi:[1,0]
	v_pk_mul_f32 v[86:87], v[50:51], v[86:87] op_sel_hi:[1,0]
	s_waitcnt vmcnt(2)
	v_mov_b64_e32 v[66:67], v[194:195]
	v_mov_b64_e32 v[68:69], v[196:197]
	v_mov_b64_e32 v[74:75], v[198:199]
	v_mov_b64_e32 v[76:77], v[200:201]
	v_mov_b64_e32 v[82:83], v[202:203]
	v_mov_b64_e32 v[84:85], v[204:205]
	v_mov_b64_e32 v[78:79], v[206:207]
	v_mov_b64_e32 v[80:81], v[208:209]
	s_mov_b32 s100, 2048
	s_mov_b32 s101, 0
	v_lshl_add_u64 v[224:225], v[224:225], 0, s[100:101]
	v_lshl_add_u64 v[226:227], v[226:227], 0, s[100:101]
	global_load_dwordx4 v[194:197], v[224:225], off offset:16
	global_load_dwordx4 v[198:201], v[224:225], off
	global_load_dwordx4 v[202:205], v[226:227], off offset:16
	global_load_dwordx4 v[206:209], v[226:227], off
	v_pk_mul_f32 v[108:109], v[84:85], v[100:101]
	v_pk_mul_f32 v[102:103], v[78:79], v[98:99]
	v_pk_mul_f32 v[104:105], v[80:81], v[96:97]
	v_pk_mul_f32 v[78:79], v[78:79], v[88:89]
	v_pk_mul_f32 v[80:81], v[80:81], v[90:91]
	v_pk_fma_f32 v[104:105], v[76:77], v[90:91], v[104:105] neg_lo:[0,0,1] neg_hi:[0,0,1]
	v_pk_mul_f32 v[106:107], v[82:83], v[86:87]
	v_pk_fma_f32 v[76:77], v[76:77], v[96:97], v[80:81]
	v_pk_fma_f32 v[80:81], v[74:75], v[98:99], v[78:79]
	v_pk_mul_f32 v[78:79], v[82:83], v[92:93]
	v_mov_b64_e32 v[82:83], s[44:45]
	v_mad_i64_i32 v[82:83], s[2:3], v70, s2, v[82:83]
	v_pk_fma_f32 v[102:103], v[74:75], v[88:89], v[102:103] neg_lo:[0,0,1] neg_hi:[0,0,1]
	v_pk_mul_f32 v[74:75], v[84:85], v[94:95]
	v_lshl_add_u64 v[82:83], s[0:1], 1, v[82:83]
	v_pk_fma_f32 v[108:109], v[68:69], v[94:95], v[108:109] neg_lo:[0,0,1] neg_hi:[0,0,1]
	v_pk_fma_f32 v[106:107], v[66:67], v[92:93], v[106:107] neg_lo:[0,0,1] neg_hi:[0,0,1]
	v_pk_fma_f32 v[74:75], v[68:69], v[100:101], v[74:75]
	v_pk_fma_f32 v[78:79], v[66:67], v[86:87], v[78:79]
	v_cvt_pk_bf16_f32 v66, v102, v103
	v_cvt_pk_bf16_f32 v67, v104, v105
	v_cvt_pk_bf16_f32 v68, v106, v107
	v_cvt_pk_bf16_f32 v69, v108, v109
	v_lshl_add_u64 v[84:85], v[82:83], 0, v[0:1]
	s_mov_b64 s[2:3], 0x140
	global_store_dwordx4 v[84:85], v[66:69], off offset:256
	s_nop 1
	v_cvt_pk_bf16_f32 v66, v80, v81
	v_cvt_pk_bf16_f32 v67, v76, v77
	v_cvt_pk_bf16_f32 v68, v78, v79
	v_cvt_pk_bf16_f32 v69, v74, v75
	v_lshl_add_u64 v[74:75], v[82:83], 0, s[2:3]

;     __device__ __forceinline__ float ssq8(int row, int which) const { const f32x4 a = *(const f32x4*)(ssqp + row * 16 + which * 8), b = *(const f32x4*)(ssqp + row * 16 + which * 8 + 4); return ((a[0] + a[1]) + (a[2] + a[3])) + ((b[0] + b[1]) + (b[2] + b[3])); }
;     __device__ __forceinline__ void operator()(const AccT& acc, const pg8::Unit& u, int wr, int wc, int fr, int fq) const {
;     ...
;                 } else if (u.pn < 6) {
;                     const float rs = rsqrtf(ssq8(row, 0) * (1.0f / 512) + EPSN) * QS_MLA;
;                     const int head = 4 * (u.pn - 4) + wc;
;                     const f32x4 c0 = *(const f32x4*)(cosT + row * 32 + 8 * fq), c1 = *(const f32x4*)(cosT + row * 32 + 8 * fq + 4);
;                     const f32x4 s0 = *(const f32x4*)(sinT + row * 32 + 8 * fq), s1 = *(const f32x4*)(sinT + row * 32 + 8 * fq + 4);
;                     const f32x4 x1a = acc[ai][0][m][0] * rs, x1b = acc[ai][0][m][1] * rs, x2a = acc[ai][1][m][0] * rs, x2b = acc[ai][1][m][1] * rs;
;                     const f32x4 y1a = x1a * c0 - x2a * s0, y1b = x1b * c1 - x2b * s1, y2a = x2a * c0 + x1a * s0, y2b = x2b * c1 + x1b * s1;
;                     *(u32x4*)(Qm + (size_t)row * 1536 + head * 192 + 128 + 8 * fq) = pack8s(y1a, y1b, 1.0f);
;                     *(u32x4*)(Qm + (size_t)row * 1536 + head * 192 + 160 + 8 * fq) = pack8s(y2a, y2b, 1.0f);
.LBB0_1471:
	s_andn2_b64 vcc, exec, s[8:9]
	s_cbranch_vccnz .LBB0_1473
	s_mov_b32 s2, 0x800000
	s_nop 0
	s_nop 0
	v_mov_b32_e32 v50, v237
	v_fmamk_f32 v50, v50, 0x3b000000, v212
	v_cmp_gt_f32_e32 vcc, s2, v50
	v_mul_f32_e32 v51, 0x4b800000, v50
	s_movk_i32 s2, 0xc00
	v_cndmask_b32_e32 v50, v50, v51, vcc
	v_rsq_f32_e32 v50, v50
	s_nop 0
	v_mul_f32_e32 v51, 0x45800000, v50
	v_cndmask_b32_e32 v50, v50, v51, vcc
	v_mul_f32_e32 v70, 0x3dd53b94, v50
	v_lshlrev_b32_e32 v50, 5, v54
	v_ashrrev_i32_e32 v51, 31, v50
	v_lshlrev_b64 v[62:63], 2, v[50:51]
	v_lshl_add_u64 v[58:59], v[144:145], 0, v[62:63]
	v_lshl_add_u64 v[62:63], v[146:147], 0, v[62:63]
	v_pk_mul_f32 v[72:73], v[46:47], v[70:71] op_sel_hi:[1,0]
	v_pk_mul_f32 v[74:75], v[48:49], v[70:71] op_sel_hi:[1,0]
	v_pk_mul_f32 v[80:81], v[40:41], v[70:71] op_sel_hi:[1,0]
	v_pk_mul_f32 v[82:83], v[38:39], v[70:71] op_sel_hi:[1,0]
	v_pk_mul_f32 v[76:77], v[42:43], v[70:71] op_sel_hi:[1,0]
	v_pk_mul_f32 v[78:79], v[44:45], v[70:71] op_sel_hi:[1,0]
	v_pk_mul_f32 v[84:85], v[36:37], v[70:71] op_sel_hi:[1,0]
	v_pk_mul_f32 v[70:71], v[34:35], v[70:71] op_sel_hi:[1,0]
	s_waitcnt vmcnt(2)
	v_mov_b64_e32 v[50:51], v[194:195]
	v_mov_b64_e32 v[52:53], v[196:197]
	v_mov_b64_e32 v[58:59], v[198:199]
	v_mov_b64_e32 v[60:61], v[200:201]
	v_mov_b64_e32 v[66:67], v[202:203]
	v_mov_b64_e32 v[68:69], v[204:205]
	v_mov_b64_e32 v[62:63], v[206:207]
	v_mov_b64_e32 v[64:65], v[208:209]
	s_mov_b32 s100, 2048
	s_mov_b32 s101, 0
	v_lshl_add_u64 v[224:225], v[224:225], 0, s[100:101]
	v_lshl_add_u64 v[226:227], v[226:227], 0, s[100:101]
	global_load_dwordx4 v[194:197], v[224:225], off offset:16
	global_load_dwordx4 v[198:201], v[224:225], off
	global_load_dwordx4 v[202:205], v[226:227], off offset:16
	global_load_dwordx4 v[206:209], v[226:227], off
	v_pk_mul_f32 v[92:93], v[68:69], v[84:85]
	v_pk_mul_f32 v[86:87], v[62:63], v[82:83]
	v_pk_mul_f32 v[88:89], v[64:65], v[80:81]
	v_pk_mul_f32 v[62:63], v[62:63], v[72:73]
	v_pk_mul_f32 v[64:65], v[64:65], v[74:75]
	v_pk_fma_f32 v[88:89], v[60:61], v[74:75], v[88:89] neg_lo:[0,0,1] neg_hi:[0,0,1]
	v_pk_mul_f32 v[90:91], v[66:67], v[70:71]
	v_pk_fma_f32 v[60:61], v[60:61], v[80:81], v[64:65]
	v_pk_fma_f32 v[64:65], v[58:59], v[82:83], v[62:63]
	v_pk_mul_f32 v[62:63], v[66:67], v[76:77]
	v_mov_b64_e32 v[66:67], s[44:45]
	v_mad_i64_i32 v[66:67], s[2:3], v54, s2, v[66:67]
	v_pk_fma_f32 v[86:87], v[58:59], v[72:73], v[86:87] neg_lo:[0,0,1] neg_hi:[0,0,1]
	v_pk_mul_f32 v[58:59], v[68:69], v[78:79]
	v_lshl_add_u64 v[66:67], s[0:1], 1, v[66:67]
	v_pk_fma_f32 v[92:93], v[52:53], v[78:79], v[92:93] neg_lo:[0,0,1] neg_hi:[0,0,1]
	v_pk_fma_f32 v[90:91], v[50:51], v[76:77], v[90:91] neg_lo:[0,0,1] neg_hi:[0,0,1]
	v_pk_fma_f32 v[58:59], v[52:53], v[84:85], v[58:59]
	v_pk_fma_f32 v[62:63], v[50:51], v[70:71], v[62:63]
	v_cvt_pk_bf16_f32 v50, v86, v87
	v_cvt_pk_bf16_f32 v51, v88, v89
	v_cvt_pk_bf16_f32 v52, v90, v91
	v_cvt_pk_bf16_f32 v53, v92, v93
	v_lshl_add_u64 v[68:69], v[66:67], 0, v[0:1]
	s_mov_b64 s[2:3], 0x140
	global_store_dwordx4 v[68:69], v[50:53], off offset:256
	s_nop 1
	v_cvt_pk_bf16_f32 v50, v64, v65
	v_cvt_pk_bf16_f32 v51, v60, v61
	v_cvt_pk_bf16_f32 v52, v62, v63
	v_cvt_pk_bf16_f32 v53, v58, v59
	v_lshl_add_u64 v[58:59], v[66:67], 0, s[2:3]

;     __device__ __forceinline__ float ssq8(int row, int which) const { const f32x4 a = *(const f32x4*)(ssqp + row * 16 + which * 8), b = *(const f32x4*)(ssqp + row * 16 + which * 8 + 4); return ((a[0] + a[1]) + (a[2] + a[3])) + ((b[0] + b[1]) + (b[2] + b[3])); }
;     __device__ __forceinline__ void operator()(const AccT& acc, const pg8::Unit& u, int wr, int wc, int fr, int fq) const {
;     ...
;                 } else if (u.pn < 6) {
;                     const float rs = rsqrtf(ssq8(row, 0) * (1.0f / 512) + EPSN) * QS_MLA;
;                     const int head = 4 * (u.pn - 4) + wc;
;                     const f32x4 c0 = *(const f32x4*)(cosT + row * 32 + 8 * fq), c1 = *(const f32x4*)(cosT + row * 32 + 8 * fq + 4);
;                     const f32x4 s0 = *(const f32x4*)(sinT + row * 32 + 8 * fq), s1 = *(const f32x4*)(sinT + row * 32 + 8 * fq + 4);
;                     const f32x4 x1a = acc[ai][0][m][0] * rs, x1b = acc[ai][0][m][1] * rs, x2a = acc[ai][1][m][0] * rs, x2b = acc[ai][1][m][1] * rs;
;                     const f32x4 y1a = x1a * c0 - x2a * s0, y1b = x1b * c1 - x2b * s1, y2a = x2a * c0 + x1a * s0, y2b = x2b * c1 + x1b * s1;
;                     *(u32x4*)(Qm + (size_t)row * 1536 + head * 192 + 128 + 8 * fq) = pack8s(y1a, y1b, 1.0f);
;                     *(u32x4*)(Qm + (size_t)row * 1536 + head * 192 + 160 + 8 * fq) = pack8s(y2a, y2b, 1.0f);
.LBB0_1479:
	s_andn2_b64 vcc, exec, s[8:9]
	s_cbranch_vccnz .LBB0_1481
	s_mov_b32 s2, 0x800000
	s_nop 0
	s_nop 0
	v_mov_b32_e32 v34, v238
	v_fmamk_f32 v34, v34, 0x3b000000, v212
	v_cmp_gt_f32_e32 vcc, s2, v34
	v_mul_f32_e32 v35, 0x4b800000, v34
	s_movk_i32 s2, 0xc00
	v_cndmask_b32_e32 v34, v34, v35, vcc
	v_rsq_f32_e32 v34, v34
	s_nop 0
	v_mul_f32_e32 v35, 0x45800000, v34
	v_cndmask_b32_e32 v34, v34, v35, vcc
	v_mul_f32_e32 v54, 0x3dd53b94, v34
	v_lshlrev_b32_e32 v34, 5, v38
	v_ashrrev_i32_e32 v35, 31, v34
	v_lshlrev_b64 v[46:47], 2, v[34:35]
	v_lshl_add_u64 v[42:43], v[144:145], 0, v[46:47]
	v_lshl_add_u64 v[46:47], v[146:147], 0, v[46:47]
	v_pk_mul_f32 v[56:57], v[30:31], v[54:55] op_sel_hi:[1,0]
	v_pk_mul_f32 v[58:59], v[32:33], v[54:55] op_sel_hi:[1,0]
	v_pk_mul_f32 v[64:65], v[24:25], v[54:55] op_sel_hi:[1,0]
	v_pk_mul_f32 v[66:67], v[22:23], v[54:55] op_sel_hi:[1,0]
	v_pk_mul_f32 v[60:61], v[26:27], v[54:55] op_sel_hi:[1,0]
	v_pk_mul_f32 v[62:63], v[28:29], v[54:55] op_sel_hi:[1,0]
	v_pk_mul_f32 v[68:69], v[20:21], v[54:55] op_sel_hi:[1,0]
	v_pk_mul_f32 v[54:55], v[18:19], v[54:55] op_sel_hi:[1,0]
	s_waitcnt vmcnt(2)
	v_mov_b64_e32 v[34:35], v[194:195]
	v_mov_b64_e32 v[36:37], v[196:197]
	v_mov_b64_e32 v[42:43], v[198:199]
	v_mov_b64_e32 v[44:45], v[200:201]
	v_mov_b64_e32 v[50:51], v[202:203]
	v_mov_b64_e32 v[52:53], v[204:205]
	v_mov_b64_e32 v[46:47], v[206:207]
	v_mov_b64_e32 v[48:49], v[208:209]
	s_mov_b32 s100, 2048
	s_mov_b32 s101, 0
	v_lshl_add_u64 v[224:225], v[224:225], 0, s[100:101]
	v_lshl_add_u64 v[226:227], v[226:227], 0, s[100:101]
	global_load_dwordx4 v[194:197], v[224:225], off offset:16
	global_load_dwordx4 v[198:201], v[224:225], off
	global_load_dwordx4 v[202:205], v[226:227], off offset:16
	global_load_dwordx4 v[206:209], v[226:227], off
	v_pk_mul_f32 v[76:77], v[52:53], v[68:69]
	v_pk_mul_f32 v[70:71], v[46:47], v[66:67]
	v_pk_mul_f32 v[72:73], v[48:49], v[64:65]
	v_pk_mul_f32 v[46:47], v[46:47], v[56:57]
	v_pk_mul_f32 v[48:49], v[48:49], v[58:59]
	v_pk_fma_f32 v[72:73], v[44:45], v[58:59], v[72:73] neg_lo:[0,0,1] neg_hi:[0,0,1]
	v_pk_mul_f32 v[74:75], v[50:51], v[54:55]
	v_pk_fma_f32 v[44:45], v[44:45], v[64:65], v[48:49]
	v_pk_fma_f32 v[48:49], v[42:43], v[66:67], v[46:47]
	v_pk_mul_f32 v[46:47], v[50:51], v[60:61]
	v_mov_b64_e32 v[50:51], s[44:45]
	v_mad_i64_i32 v[50:51], s[2:3], v38, s2, v[50:51]
	v_pk_fma_f32 v[70:71], v[42:43], v[56:57], v[70:71] neg_lo:[0,0,1] neg_hi:[0,0,1]
	v_pk_mul_f32 v[42:43], v[52:53], v[62:63]
	v_lshl_add_u64 v[50:51], s[0:1], 1, v[50:51]
	v_pk_fma_f32 v[76:77], v[36:37], v[62:63], v[76:77] neg_lo:[0,0,1] neg_hi:[0,0,1]
	v_pk_fma_f32 v[74:75], v[34:35], v[60:61], v[74:75] neg_lo:[0,0,1] neg_hi:[0,0,1]
	v_pk_fma_f32 v[42:43], v[36:37], v[68:69], v[42:43]
	v_pk_fma_f32 v[46:47], v[34:35], v[54:55], v[46:47]
	v_cvt_pk_bf16_f32 v34, v70, v71
	v_cvt_pk_bf16_f32 v35, v72, v73
	v_cvt_pk_bf16_f32 v36, v74, v75
	v_cvt_pk_bf16_f32 v37, v76, v77
	v_lshl_add_u64 v[52:53], v[50:51], 0, v[0:1]
	s_mov_b64 s[2:3], 0x140
	global_store_dwordx4 v[52:53], v[34:37], off offset:256
	s_nop 1
	v_cvt_pk_bf16_f32 v34, v48, v49
	v_cvt_pk_bf16_f32 v35, v44, v45
	v_cvt_pk_bf16_f32 v36, v46, v47
	v_cvt_pk_bf16_f32 v37, v42, v43
	v_lshl_add_u64 v[42:43], v[50:51], 0, s[2:3]

;     __device__ __forceinline__ float ssq8(int row, int which) const { const f32x4 a = *(const f32x4*)(ssqp + row * 16 + which * 8), b = *(const f32x4*)(ssqp + row * 16 + which * 8 + 4); return ((a[0] + a[1]) + (a[2] + a[3])) + ((b[0] + b[1]) + (b[2] + b[3])); }
;     __device__ __forceinline__ void operator()(const AccT& acc, const pg8::Unit& u, int wr, int wc, int fr, int fq) const {
;     ...
;                 } else if (u.pn < 6) {
;                     const float rs = rsqrtf(ssq8(row, 0) * (1.0f / 512) + EPSN) * QS_MLA;
;                     const int head = 4 * (u.pn - 4) + wc;
;                     const f32x4 c0 = *(const f32x4*)(cosT + row * 32 + 8 * fq), c1 = *(const f32x4*)(cosT + row * 32 + 8 * fq + 4);
;                     const f32x4 s0 = *(const f32x4*)(sinT + row * 32 + 8 * fq), s1 = *(const f32x4*)(sinT + row * 32 + 8 * fq + 4);
;                     const f32x4 x1a = acc[ai][0][m][0] * rs, x1b = acc[ai][0][m][1] * rs, x2a = acc[ai][1][m][0] * rs, x2b = acc[ai][1][m][1] * rs;
;                     const f32x4 y1a = x1a * c0 - x2a * s0, y1b = x1b * c1 - x2b * s1, y2a = x2a * c0 + x1a * s0, y2b = x2b * c1 + x1b * s1;
;                     *(u32x4*)(Qm + (size_t)row * 1536 + head * 192 + 128 + 8 * fq) = pack8s(y1a, y1b, 1.0f);
;                     *(u32x4*)(Qm + (size_t)row * 1536 + head * 192 + 160 + 8 * fq) = pack8s(y2a, y2b, 1.0f);
.LBB0_1487:
	s_andn2_b64 vcc, exec, s[8:9]
	s_cbranch_vccnz .LBB0_1489
	s_mov_b32 s2, 0x800000
	s_nop 0
	s_nop 0
	v_mov_b32_e32 v18, v239
	v_fmamk_f32 v18, v18, 0x3b000000, v212
	v_cmp_gt_f32_e32 vcc, s2, v18
	v_mul_f32_e32 v19, 0x4b800000, v18
	s_movk_i32 s2, 0xc00
	v_cndmask_b32_e32 v18, v18, v19, vcc
	v_rsq_f32_e32 v18, v18
	s_nop 0
	v_mul_f32_e32 v19, 0x45800000, v18
	v_cndmask_b32_e32 v18, v18, v19, vcc
	v_mul_f32_e32 v38, 0x3dd53b94, v18
	v_lshlrev_b32_e32 v18, 5, v22
	v_ashrrev_i32_e32 v19, 31, v18
	v_lshlrev_b64 v[30:31], 2, v[18:19]
	v_lshl_add_u64 v[26:27], v[144:145], 0, v[30:31]
	v_lshl_add_u64 v[30:31], v[146:147], 0, v[30:31]
	v_pk_mul_f32 v[40:41], v[14:15], v[38:39] op_sel_hi:[1,0]
	v_pk_mul_f32 v[42:43], v[16:17], v[38:39] op_sel_hi:[1,0]
	v_pk_mul_f32 v[48:49], v[8:9], v[38:39] op_sel_hi:[1,0]
	v_pk_mul_f32 v[50:51], v[6:7], v[38:39] op_sel_hi:[1,0]
	v_pk_mul_f32 v[44:45], v[10:11], v[38:39] op_sel_hi:[1,0]
	v_pk_mul_f32 v[46:47], v[12:13], v[38:39] op_sel_hi:[1,0]
	v_pk_mul_f32 v[52:53], v[4:5], v[38:39] op_sel_hi:[1,0]
	v_pk_mul_f32 v[38:39], v[2:3], v[38:39] op_sel_hi:[1,0]
	s_waitcnt vmcnt(2)
	v_mov_b64_e32 v[18:19], v[194:195]
	v_mov_b64_e32 v[20:21], v[196:197]
	v_mov_b64_e32 v[26:27], v[198:199]
	v_mov_b64_e32 v[28:29], v[200:201]
	v_mov_b64_e32 v[34:35], v[202:203]
	v_mov_b64_e32 v[36:37], v[204:205]
	v_mov_b64_e32 v[30:31], v[206:207]
	v_mov_b64_e32 v[32:33], v[208:209]
	v_pk_mul_f32 v[60:61], v[36:37], v[52:53]
	v_pk_mul_f32 v[54:55], v[30:31], v[50:51]
	v_pk_mul_f32 v[56:57], v[32:33], v[48:49]
	v_pk_mul_f32 v[30:31], v[30:31], v[40:41]
	v_pk_mul_f32 v[32:33], v[32:33], v[42:43]
	v_pk_fma_f32 v[56:57], v[28:29], v[42:43], v[56:57] neg_lo:[0,0,1] neg_hi:[0,0,1]
	v_pk_mul_f32 v[58:59], v[34:35], v[38:39]
	v_pk_fma_f32 v[28:29], v[28:29], v[48:49], v[32:33]
	v_pk_fma_f32 v[32:33], v[26:27], v[50:51], v[30:31]
	v_pk_mul_f32 v[30:31], v[34:35], v[44:45]
	v_mov_b64_e32 v[34:35], s[44:45]
	v_mad_i64_i32 v[34:35], s[2:3], v22, s2, v[34:35]
	v_pk_fma_f32 v[54:55], v[26:27], v[40:41], v[54:55] neg_lo:[0,0,1] neg_hi:[0,0,1]
	v_pk_mul_f32 v[26:27], v[36:37], v[46:47]
	v_lshl_add_u64 v[34:35], s[0:1], 1, v[34:35]
	v_pk_fma_f32 v[60:61], v[20:21], v[46:47], v[60:61] neg_lo:[0,0,1] neg_hi:[0,0,1]
	v_pk_fma_f32 v[58:59], v[18:19], v[44:45], v[58:59] neg_lo:[0,0,1] neg_hi:[0,0,1]
	v_pk_fma_f32 v[26:27], v[20:21], v[52:53], v[26:27]
	v_pk_fma_f32 v[30:31], v[18:19], v[38:39], v[30:31]
	v_cvt_pk_bf16_f32 v18, v54, v55
	v_cvt_pk_bf16_f32 v19, v56, v57
	v_cvt_pk_bf16_f32 v20, v58, v59
	v_cvt_pk_bf16_f32 v21, v60, v61
	v_lshl_add_u64 v[36:37], v[34:35], 0, v[0:1]
	s_mov_b64 s[0:1], 0x140
	global_store_dwordx4 v[36:37], v[18:21], off offset:256
	s_nop 1
	v_cvt_pk_bf16_f32 v18, v32, v33
	v_cvt_pk_bf16_f32 v19, v28, v29
	v_cvt_pk_bf16_f32 v20, v30, v31
	v_cvt_pk_bf16_f32 v21, v26, v27
	v_lshl_add_u64 v[26:27], v[34:35], 0, s[0:1]
